# phase 0 row pass: conflict-free LDS layout for the wab table (row k at 32k+16(k>>2)); 8-way ds_read_b128 bank conflict removed
# speedup vs baseline: 1.0125x; 1.0125x over previous
.LBB0_164:
	s_waitcnt lgkmcnt(0)
	v_lshrrev_b32_e32 v100, 3, v8
	v_and_b32_e32 v101, 7, v8
	v_lshlrev_b32_e32 v102, 2, v100
	global_load_dword v104, v102, s[28:29]
	global_load_dword v105, v102, s[28:29] offset:256
	global_load_dword v106, v102, s[28:29] offset:512
	global_load_dword v107, v102, s[28:29] offset:768
	global_load_dword v108, v102, s[28:29] offset:1024
	global_load_dword v109, v102, s[28:29] offset:1280
	global_load_dword v110, v102, s[28:29] offset:1536
	global_load_dword v111, v102, s[28:29] offset:1792
	global_load_dword v112, v102, s[28:29] offset:2048
	global_load_dword v113, v102, s[28:29] offset:2304
	global_load_dword v114, v102, s[28:29] offset:2560
	global_load_dword v115, v102, s[28:29] offset:2816
	global_load_dword v116, v102, s[28:29] offset:3072
	global_load_dword v117, v102, s[28:29] offset:3328
	global_load_dword v118, v102, s[28:29] offset:3584
	global_load_dword v119, v102, s[28:29] offset:3840
	v_mul_u32_u24_e32 v120, 0x7820, v100
	v_lshl_add_u32 v120, v101, 2, v120
	v_add_u32_e32 v120, 0x4000, v120
	global_load_dword v124, v120, s[30:31]
	v_add_u32_e32 v120, 0x1e0800, v120
	global_load_dword v125, v120, s[30:31]
	v_add_u32_e32 v120, 0x1e0800, v120
	global_load_dword v126, v120, s[30:31]
	v_add_u32_e32 v120, 0x1e0800, v120
	global_load_dword v127, v120, s[30:31]
	v_add_u32_e32 v120, 0x1e0800, v120
	global_load_dword v128, v120, s[30:31]
	v_add_u32_e32 v120, 0x1e0800, v120
	global_load_dword v129, v120, s[30:31]
	v_add_u32_e32 v120, 0x1e0800, v120
	global_load_dword v130, v120, s[30:31]
	v_add_u32_e32 v120, 0x1e0800, v120
	global_load_dword v131, v120, s[30:31]
	v_add_u32_e32 v120, 0x1e0800, v120
	global_load_dword v132, v120, s[30:31]
	v_add_u32_e32 v120, 0x1e0800, v120
	global_load_dword v133, v120, s[30:31]
	v_add_u32_e32 v120, 0x1e0800, v120
	global_load_dword v134, v120, s[30:31]
	v_add_u32_e32 v120, 0x1e0800, v120
	global_load_dword v135, v120, s[30:31]
	v_add_u32_e32 v120, 0x1e0800, v120
	global_load_dword v136, v120, s[30:31]
	v_add_u32_e32 v120, 0x1e0800, v120
	global_load_dword v137, v120, s[30:31]
	v_add_u32_e32 v120, 0x1e0800, v120
	global_load_dword v138, v120, s[30:31]
	v_add_u32_e32 v120, 0x1e0800, v120
	global_load_dword v139, v120, s[30:31]
	v_lshrrev_b32_e32 v122, 5, v8
	v_lshlrev_b32_e32 v121, 2, v8
	v_lshl_add_u32 v121, v122, 4, v121
	s_waitcnt vmcnt(0)
	v_mul_f32_e32 v104, v104, v124
	v_mul_f32_e32 v105, v105, v125
	v_mul_f32_e32 v106, v106, v126
	v_mul_f32_e32 v107, v107, v127
	v_mul_f32_e32 v108, v108, v128
	v_mul_f32_e32 v109, v109, v129
	v_mul_f32_e32 v110, v110, v130
	v_mul_f32_e32 v111, v111, v131
	v_mul_f32_e32 v112, v112, v132
	v_mul_f32_e32 v113, v113, v133
	v_mul_f32_e32 v114, v114, v134
	v_mul_f32_e32 v115, v115, v135
	v_mul_f32_e32 v116, v116, v136
	v_mul_f32_e32 v117, v117, v137
	v_mul_f32_e32 v118, v118, v138
	v_mul_f32_e32 v119, v119, v139
	ds_write_b32 v121, v104
	ds_write_b32 v121, v105 offset:2304
	ds_write_b32 v121, v106 offset:4608
	ds_write_b32 v121, v107 offset:6912
	ds_write_b32 v121, v108 offset:9216
	ds_write_b32 v121, v109 offset:11520
	ds_write_b32 v121, v110 offset:13824
	ds_write_b32 v121, v111 offset:16128
	ds_write_b32 v121, v112 offset:18432
	ds_write_b32 v121, v113 offset:20736
	ds_write_b32 v121, v114 offset:23040
	ds_write_b32 v121, v115 offset:25344
	ds_write_b32 v121, v116 offset:27648
	ds_write_b32 v121, v117 offset:29952
	ds_write_b32 v121, v118 offset:32256
	ds_write_b32 v121, v119 offset:34560
.LBB0_176:
	s_or_b64 exec, exec, s[4:5]
	v_ashrrev_i32_e32 v0, 6, v8
	v_lshl_add_u32 v46, s2, 3, v0
	s_movk_i32 s2, 0x4a00
	v_cmp_gt_i32_e32 vcc, s2, v46
	s_waitcnt lgkmcnt(0)
	s_barrier
	s_and_saveexec_b64 s[12:13], vcc
	s_cbranch_execz .LBB0_229
	s_add_u32 s3, s24, 0x4e24000
	s_addc_u32 s10, s25, 0
	s_add_u32 s11, s26, 0x1830000
	s_addc_u32 s33, s27, 0
	s_add_u32 s14, s26, 0x1600000
	s_addc_u32 s15, s27, 0
	v_and_b32_e32 v0, 63, v8
	s_add_u32 s16, s26, 0x1612800
	v_lshlrev_b32_e32 v40, 2, v0
	v_mul_u32_u24_e32 v41, 0x90, v0
	s_addc_u32 s17, s27, 0
	s_lshl_b32 s42, s34, 3
	v_mov_b32_e32 v43, 0
	v_cmp_eq_u32_e64 s[4:5], 0, v0
	v_add_u32_e32 v52, 0x2400, v41
	v_add_u32_e32 v53, 0x4800, v41
	v_add_u32_e32 v54, 0x6c00, v41
	s_mov_b64 s[18:19], 0
	s_movk_i32 s43, 0x3fff
	s_movk_i32 s56, 0x41ff
	v_lshlrev_b32_e32 v42, 2, v40
	s_movk_i32 s57, 0x4200
	s_movk_i32 s58, 0x7fff
	v_mov_b32_e32 v55, 0x358637bd
	s_mov_b32 s59, 0x800000
	s_movk_i32 s60, 0x49ff
	v_mov_b32_e32 v56, 1
	s_branch .LBB0_179

.LBB0_199:
	s_or_b64 exec, exec, s[24:25]
	s_waitcnt vmcnt(3)
	v_and_b32_sdwa v58, v35, v56 dst_sel:DWORD dst_unused:UNUSED_PAD src0_sel:WORD_1 src1_sel:DWORD
	v_and_b32_sdwa v59, v33, v56 dst_sel:DWORD dst_unused:UNUSED_PAD src0_sel:WORD_1 src1_sel:DWORD
	v_and_b32_sdwa v45, v34, v56 dst_sel:DWORD dst_unused:UNUSED_PAD src0_sel:WORD_1 src1_sel:DWORD
	v_and_b32_sdwa v49, v32, v56 dst_sel:DWORD dst_unused:UNUSED_PAD src0_sel:WORD_1 src1_sel:DWORD
	v_add3_u32 v58, v35, v58, s58
	v_add3_u32 v59, v33, v59, s58
	v_add3_u32 v49, v32, v49, s58
	v_add3_u32 v45, v34, v45, s58
	v_and_b32_e32 v58, 0xffff0000, v58
	v_and_b32_e32 v60, 0xffff0000, v59
	v_or_b32_sdwa v59, v58, v45 dst_sel:DWORD dst_unused:UNUSED_PAD src0_sel:DWORD src1_sel:WORD_1
	v_or_b32_sdwa v58, v60, v49 dst_sel:DWORD dst_unused:UNUSED_PAD src0_sel:DWORD src1_sel:WORD_1
	global_store_dwordx2 v[50:51], v[58:59], off offset:512
	s_and_saveexec_b64 s[24:25], s[8:9]
	s_cbranch_execz .LBB0_201
	v_add_u32_e32 v45, 0, v52
	ds_read_b128 v[58:61], v45 offset:16
	ds_read_b128 v[62:65], v57 offset:9248
	ds_read_b128 v[66:69], v57 offset:9264
	ds_read_b128 v[70:73], v45
	ds_read_b128 v[74:77], v57 offset:9280
	ds_read_b128 v[78:81], v57 offset:9296
	ds_read_b128 v[82:85], v57 offset:9312
	ds_read_b128 v[86:89], v57 offset:9328
	s_waitcnt lgkmcnt(7)
	v_mul_f32_e32 v60, v32, v60
	s_waitcnt lgkmcnt(5)
	v_mul_f32_e32 v90, v33, v68
	v_mov_b32_e32 v68, v61
	v_pk_mul_f32 v[68:69], v[32:33], v[68:69]
	s_waitcnt lgkmcnt(0)
	v_mul_f32_e32 v94, v35, v88
	v_mov_b32_e32 v88, v81
	v_mov_b32_e32 v61, v68
	v_pk_mul_f32 v[88:89], v[34:35], v[88:89]
	v_pk_fma_f32 v[4:5], v[32:33], v[58:59], v[4:5] op_sel_hi:[0,1,1]
	v_pk_add_f32 v[6:7], v[6:7], v[60:61]
	v_pk_fma_f32 v[2:3], v[32:33], v[72:73], v[2:3] op_sel_hi:[0,1,1]
	v_pk_fma_f32 v[0:1], v[32:33], v[70:71], v[0:1] op_sel_hi:[0,1,1]
	v_mov_b32_e32 v91, v69
	v_mul_f32_e32 v80, v34, v80
	v_pk_fma_f32 v[2:3], v[32:33], v[64:65], v[2:3] op_sel:[1,0,0]
	v_pk_add_f32 v[6:7], v[6:7], v[90:91]
	v_pk_fma_f32 v[4:5], v[32:33], v[66:67], v[4:5] op_sel:[1,0,0]
	v_pk_fma_f32 v[0:1], v[32:33], v[62:63], v[0:1] op_sel:[1,0,0]
	v_mov_b32_e32 v81, v88
	v_mov_b32_e32 v92, v35
	v_pk_add_f32 v[6:7], v[6:7], v[80:81]
	v_pk_fma_f32 v[2:3], v[34:35], v[76:77], v[2:3] op_sel_hi:[0,1,1]
	v_pk_fma_f32 v[0:1], v[34:35], v[74:75], v[0:1] op_sel_hi:[0,1,1]
	v_pk_fma_f32 v[4:5], v[34:35], v[78:79], v[4:5] op_sel_hi:[0,1,1]
	v_mov_b32_e32 v95, v89
	v_pk_fma_f32 v[2:3], v[92:93], v[84:85], v[2:3] op_sel_hi:[0,1,1]
	v_pk_add_f32 v[6:7], v[6:7], v[94:95]
	v_pk_fma_f32 v[4:5], v[92:93], v[86:87], v[4:5] op_sel_hi:[0,1,1]
	v_pk_fma_f32 v[0:1], v[92:93], v[82:83], v[0:1] op_sel_hi:[0,1,1]
.LBB0_201:
	s_or_b64 exec, exec, s[24:25]
	s_waitcnt vmcnt(3)
	v_and_b32_sdwa v58, v31, v56 dst_sel:DWORD dst_unused:UNUSED_PAD src0_sel:WORD_1 src1_sel:DWORD
	v_and_b32_sdwa v59, v29, v56 dst_sel:DWORD dst_unused:UNUSED_PAD src0_sel:WORD_1 src1_sel:DWORD
	v_and_b32_sdwa v45, v30, v56 dst_sel:DWORD dst_unused:UNUSED_PAD src0_sel:WORD_1 src1_sel:DWORD
	v_and_b32_sdwa v49, v28, v56 dst_sel:DWORD dst_unused:UNUSED_PAD src0_sel:WORD_1 src1_sel:DWORD
	v_add3_u32 v58, v31, v58, s58
	v_add3_u32 v59, v29, v59, s58
	v_add3_u32 v49, v28, v49, s58
	v_add3_u32 v45, v30, v45, s58
	v_and_b32_e32 v58, 0xffff0000, v58
	v_and_b32_e32 v60, 0xffff0000, v59
	v_or_b32_sdwa v59, v58, v45 dst_sel:DWORD dst_unused:UNUSED_PAD src0_sel:DWORD src1_sel:WORD_1
	v_or_b32_sdwa v58, v60, v49 dst_sel:DWORD dst_unused:UNUSED_PAD src0_sel:DWORD src1_sel:WORD_1
	global_store_dwordx2 v[50:51], v[58:59], off offset:1024
	s_and_saveexec_b64 s[24:25], s[8:9]
	s_cbranch_execz .LBB0_203
	v_add_u32_e32 v45, 0, v53
	ds_read_b128 v[58:61], v45 offset:16
	ds_read_b128 v[62:65], v57 offset:18464
	ds_read_b128 v[66:69], v57 offset:18480
	ds_read_b128 v[70:73], v45
	ds_read_b128 v[74:77], v57 offset:18496
	ds_read_b128 v[78:81], v57 offset:18512
	ds_read_b128 v[82:85], v57 offset:18528
	ds_read_b128 v[86:89], v57 offset:18544
	s_waitcnt lgkmcnt(7)
	v_mul_f32_e32 v60, v28, v60
	s_waitcnt lgkmcnt(5)
	v_mul_f32_e32 v90, v29, v68
	v_mov_b32_e32 v68, v61
	v_pk_mul_f32 v[68:69], v[28:29], v[68:69]
	s_waitcnt lgkmcnt(0)
	v_mul_f32_e32 v94, v31, v88
	v_mov_b32_e32 v88, v81
	v_mov_b32_e32 v61, v68
	v_pk_mul_f32 v[88:89], v[30:31], v[88:89]
	v_pk_fma_f32 v[4:5], v[28:29], v[58:59], v[4:5] op_sel_hi:[0,1,1]
	v_pk_add_f32 v[6:7], v[6:7], v[60:61]
	v_pk_fma_f32 v[2:3], v[28:29], v[72:73], v[2:3] op_sel_hi:[0,1,1]
	v_pk_fma_f32 v[0:1], v[28:29], v[70:71], v[0:1] op_sel_hi:[0,1,1]
	v_mov_b32_e32 v91, v69
	v_mul_f32_e32 v80, v30, v80
	v_pk_fma_f32 v[2:3], v[28:29], v[64:65], v[2:3] op_sel:[1,0,0]
	v_pk_add_f32 v[6:7], v[6:7], v[90:91]
	v_pk_fma_f32 v[4:5], v[28:29], v[66:67], v[4:5] op_sel:[1,0,0]
	v_pk_fma_f32 v[0:1], v[28:29], v[62:63], v[0:1] op_sel:[1,0,0]
	v_mov_b32_e32 v81, v88
	v_mov_b32_e32 v92, v31
	v_pk_add_f32 v[6:7], v[6:7], v[80:81]
	v_pk_fma_f32 v[2:3], v[30:31], v[76:77], v[2:3] op_sel_hi:[0,1,1]
	v_pk_fma_f32 v[0:1], v[30:31], v[74:75], v[0:1] op_sel_hi:[0,1,1]
	v_pk_fma_f32 v[4:5], v[30:31], v[78:79], v[4:5] op_sel_hi:[0,1,1]
	v_mov_b32_e32 v95, v89
	v_pk_fma_f32 v[2:3], v[92:93], v[84:85], v[2:3] op_sel_hi:[0,1,1]
	v_pk_add_f32 v[6:7], v[6:7], v[94:95]
	v_pk_fma_f32 v[4:5], v[92:93], v[86:87], v[4:5] op_sel_hi:[0,1,1]
	v_pk_fma_f32 v[0:1], v[92:93], v[82:83], v[0:1] op_sel_hi:[0,1,1]
.LBB0_203:
	s_or_b64 exec, exec, s[24:25]
	s_waitcnt vmcnt(3)
	v_and_b32_sdwa v58, v27, v56 dst_sel:DWORD dst_unused:UNUSED_PAD src0_sel:WORD_1 src1_sel:DWORD
	v_and_b32_sdwa v59, v25, v56 dst_sel:DWORD dst_unused:UNUSED_PAD src0_sel:WORD_1 src1_sel:DWORD
	v_and_b32_sdwa v45, v26, v56 dst_sel:DWORD dst_unused:UNUSED_PAD src0_sel:WORD_1 src1_sel:DWORD
	v_and_b32_sdwa v49, v24, v56 dst_sel:DWORD dst_unused:UNUSED_PAD src0_sel:WORD_1 src1_sel:DWORD
	v_add3_u32 v58, v27, v58, s58
	v_add3_u32 v59, v25, v59, s58
	v_add3_u32 v49, v24, v49, s58
	v_add3_u32 v45, v26, v45, s58
	v_and_b32_e32 v58, 0xffff0000, v58
	v_and_b32_e32 v60, 0xffff0000, v59
	v_or_b32_sdwa v59, v58, v45 dst_sel:DWORD dst_unused:UNUSED_PAD src0_sel:DWORD src1_sel:WORD_1
	v_or_b32_sdwa v58, v60, v49 dst_sel:DWORD dst_unused:UNUSED_PAD src0_sel:DWORD src1_sel:WORD_1
	global_store_dwordx2 v[50:51], v[58:59], off offset:1536
	s_and_saveexec_b64 s[24:25], s[8:9]
	s_cbranch_execz .LBB0_205
	v_add_u32_e32 v45, 0, v54
	ds_read_b128 v[58:61], v45 offset:16
	ds_read_b128 v[62:65], v57 offset:27680
	ds_read_b128 v[66:69], v57 offset:27696
	ds_read_b128 v[70:73], v45
	ds_read_b128 v[74:77], v57 offset:27712
	ds_read_b128 v[78:81], v57 offset:27728
	ds_read_b128 v[82:85], v57 offset:27744
	ds_read_b128 v[86:89], v57 offset:27760
	s_waitcnt lgkmcnt(7)
	v_mul_f32_e32 v50, v24, v60
	s_waitcnt lgkmcnt(5)
	v_mul_f32_e32 v60, v25, v68
	v_mov_b32_e32 v68, v61
	v_pk_mul_f32 v[68:69], v[24:25], v[68:69]
	s_waitcnt lgkmcnt(0)
	v_mul_f32_e32 v92, v27, v88
	v_mov_b32_e32 v88, v81
	v_mov_b32_e32 v51, v68
	v_pk_mul_f32 v[88:89], v[26:27], v[88:89]
	v_pk_fma_f32 v[4:5], v[24:25], v[58:59], v[4:5] op_sel_hi:[0,1,1]
	v_pk_add_f32 v[6:7], v[6:7], v[50:51]
	v_pk_fma_f32 v[2:3], v[24:25], v[72:73], v[2:3] op_sel_hi:[0,1,1]
	v_pk_fma_f32 v[0:1], v[24:25], v[70:71], v[0:1] op_sel_hi:[0,1,1]
	v_mov_b32_e32 v61, v69
	v_mul_f32_e32 v80, v26, v80
	v_pk_fma_f32 v[2:3], v[24:25], v[64:65], v[2:3] op_sel:[1,0,0]
	v_pk_add_f32 v[6:7], v[6:7], v[60:61]
	v_pk_fma_f32 v[4:5], v[24:25], v[66:67], v[4:5] op_sel:[1,0,0]
	v_pk_fma_f32 v[0:1], v[24:25], v[62:63], v[0:1] op_sel:[1,0,0]
	v_mov_b32_e32 v81, v88
	v_mov_b32_e32 v90, v27
	v_pk_add_f32 v[6:7], v[6:7], v[80:81]
	v_pk_fma_f32 v[2:3], v[26:27], v[76:77], v[2:3] op_sel_hi:[0,1,1]
	v_pk_fma_f32 v[0:1], v[26:27], v[74:75], v[0:1] op_sel_hi:[0,1,1]
	v_pk_fma_f32 v[4:5], v[26:27], v[78:79], v[4:5] op_sel_hi:[0,1,1]
	v_mov_b32_e32 v93, v89
	v_pk_fma_f32 v[2:3], v[90:91], v[84:85], v[2:3] op_sel_hi:[0,1,1]
	v_pk_add_f32 v[6:7], v[6:7], v[92:93]
	v_pk_fma_f32 v[4:5], v[90:91], v[86:87], v[4:5] op_sel_hi:[0,1,1]
	v_pk_fma_f32 v[0:1], v[90:91], v[82:83], v[0:1] op_sel_hi:[0,1,1]

.LBB0_216:
	s_or_b64 exec, exec, s[24:25]
	v_and_b32_sdwa v27, v12, v56 dst_sel:DWORD dst_unused:UNUSED_PAD src0_sel:WORD_1 src1_sel:DWORD
	v_add3_u32 v28, v12, v27, s58
	v_and_b32_sdwa v27, v15, v56 dst_sel:DWORD dst_unused:UNUSED_PAD src0_sel:WORD_1 src1_sel:DWORD
	v_and_b32_sdwa v29, v13, v56 dst_sel:DWORD dst_unused:UNUSED_PAD src0_sel:WORD_1 src1_sel:DWORD
	v_and_b32_sdwa v26, v14, v56 dst_sel:DWORD dst_unused:UNUSED_PAD src0_sel:WORD_1 src1_sel:DWORD
	v_add3_u32 v27, v15, v27, s58
	v_add3_u32 v29, v13, v29, s58
	v_add3_u32 v26, v14, v26, s58
	v_and_b32_e32 v27, 0xffff0000, v27
	v_and_b32_e32 v29, 0xffff0000, v29
	v_or_b32_sdwa v27, v27, v26 dst_sel:DWORD dst_unused:UNUSED_PAD src0_sel:DWORD src1_sel:WORD_1
	v_or_b32_sdwa v26, v29, v28 dst_sel:DWORD dst_unused:UNUSED_PAD src0_sel:DWORD src1_sel:WORD_1
	global_store_dwordx2 v[24:25], v[26:27], off offset:512
	s_and_saveexec_b64 s[24:25], s[6:7]
	s_cbranch_execz .LBB0_218
	v_add_u32_e32 v38, 0, v52
	ds_read_b128 v[26:29], v38 offset:16
	ds_read_b128 v[30:33], v57 offset:9248
	ds_read_b128 v[34:37], v57 offset:9264
	ds_read_b128 v[46:49], v38
	ds_read_b128 v[58:61], v57 offset:9280
	ds_read_b128 v[62:65], v57 offset:9296
	ds_read_b128 v[66:69], v57 offset:9312
	ds_read_b128 v[70:73], v57 offset:9328
	s_waitcnt lgkmcnt(7)
	v_mul_f32_e32 v28, v12, v28
	s_waitcnt lgkmcnt(5)
	v_mul_f32_e32 v38, v13, v36
	v_mov_b32_e32 v36, v29
	v_pk_mul_f32 v[36:37], v[12:13], v[36:37]
	s_waitcnt lgkmcnt(0)
	v_mul_f32_e32 v74, v15, v72
	v_mov_b32_e32 v72, v65
	v_mov_b32_e32 v29, v36
	v_pk_mul_f32 v[72:73], v[14:15], v[72:73]
	v_pk_fma_f32 v[4:5], v[12:13], v[26:27], v[4:5] op_sel_hi:[0,1,1]
	v_pk_add_f32 v[6:7], v[6:7], v[28:29]
	v_pk_fma_f32 v[2:3], v[12:13], v[48:49], v[2:3] op_sel_hi:[0,1,1]
	v_pk_fma_f32 v[0:1], v[12:13], v[46:47], v[0:1] op_sel_hi:[0,1,1]
	v_mov_b32_e32 v39, v37
	v_mul_f32_e32 v50, v14, v64
	v_pk_fma_f32 v[2:3], v[12:13], v[32:33], v[2:3] op_sel:[1,0,0]
	v_pk_add_f32 v[6:7], v[6:7], v[38:39]
	v_pk_fma_f32 v[4:5], v[12:13], v[34:35], v[4:5] op_sel:[1,0,0]
	v_pk_fma_f32 v[0:1], v[12:13], v[30:31], v[0:1] op_sel:[1,0,0]
	v_mov_b32_e32 v51, v72
	v_mov_b32_e32 v64, v15
	v_pk_add_f32 v[6:7], v[6:7], v[50:51]
	v_pk_fma_f32 v[2:3], v[14:15], v[60:61], v[2:3] op_sel_hi:[0,1,1]
	v_pk_fma_f32 v[0:1], v[14:15], v[58:59], v[0:1] op_sel_hi:[0,1,1]
	v_pk_fma_f32 v[4:5], v[14:15], v[62:63], v[4:5] op_sel_hi:[0,1,1]
	v_mov_b32_e32 v75, v73
	v_pk_fma_f32 v[2:3], v[64:65], v[68:69], v[2:3] op_sel_hi:[0,1,1]
	v_pk_add_f32 v[6:7], v[6:7], v[74:75]
	v_pk_fma_f32 v[4:5], v[64:65], v[70:71], v[4:5] op_sel_hi:[0,1,1]
	v_pk_fma_f32 v[0:1], v[64:65], v[66:67], v[0:1] op_sel_hi:[0,1,1]
.LBB0_218:
	s_or_b64 exec, exec, s[24:25]
	v_and_b32_sdwa v27, v16, v56 dst_sel:DWORD dst_unused:UNUSED_PAD src0_sel:WORD_1 src1_sel:DWORD
	v_add3_u32 v28, v16, v27, s58
	v_and_b32_sdwa v27, v19, v56 dst_sel:DWORD dst_unused:UNUSED_PAD src0_sel:WORD_1 src1_sel:DWORD
	v_and_b32_sdwa v29, v17, v56 dst_sel:DWORD dst_unused:UNUSED_PAD src0_sel:WORD_1 src1_sel:DWORD
	v_and_b32_sdwa v26, v18, v56 dst_sel:DWORD dst_unused:UNUSED_PAD src0_sel:WORD_1 src1_sel:DWORD
	v_add3_u32 v27, v19, v27, s58
	v_add3_u32 v29, v17, v29, s58
	v_add3_u32 v26, v18, v26, s58
	v_and_b32_e32 v27, 0xffff0000, v27
	v_and_b32_e32 v29, 0xffff0000, v29
	v_or_b32_sdwa v27, v27, v26 dst_sel:DWORD dst_unused:UNUSED_PAD src0_sel:DWORD src1_sel:WORD_1
	v_or_b32_sdwa v26, v29, v28 dst_sel:DWORD dst_unused:UNUSED_PAD src0_sel:DWORD src1_sel:WORD_1
	global_store_dwordx2 v[24:25], v[26:27], off offset:1024
	s_and_saveexec_b64 s[24:25], s[6:7]
	s_cbranch_execz .LBB0_220
	v_add_u32_e32 v38, 0, v53
	ds_read_b128 v[26:29], v38 offset:16
	ds_read_b128 v[30:33], v57 offset:18464
	ds_read_b128 v[34:37], v57 offset:18480
	ds_read_b128 v[46:49], v38
	ds_read_b128 v[58:61], v57 offset:18496
	ds_read_b128 v[62:65], v57 offset:18512
	ds_read_b128 v[66:69], v57 offset:18528
	ds_read_b128 v[70:73], v57 offset:18544
	s_waitcnt lgkmcnt(7)
	v_mul_f32_e32 v28, v16, v28
	s_waitcnt lgkmcnt(5)
	v_mul_f32_e32 v38, v17, v36
	v_mov_b32_e32 v36, v29
	v_pk_mul_f32 v[36:37], v[16:17], v[36:37]
	s_waitcnt lgkmcnt(0)
	v_mul_f32_e32 v74, v19, v72
	v_mov_b32_e32 v72, v65
	v_mov_b32_e32 v29, v36
	v_pk_mul_f32 v[72:73], v[18:19], v[72:73]
	v_pk_fma_f32 v[4:5], v[16:17], v[26:27], v[4:5] op_sel_hi:[0,1,1]
	v_pk_add_f32 v[6:7], v[6:7], v[28:29]
	v_pk_fma_f32 v[2:3], v[16:17], v[48:49], v[2:3] op_sel_hi:[0,1,1]
	v_pk_fma_f32 v[0:1], v[16:17], v[46:47], v[0:1] op_sel_hi:[0,1,1]
	v_mov_b32_e32 v39, v37
	v_mul_f32_e32 v50, v18, v64
	v_pk_fma_f32 v[2:3], v[16:17], v[32:33], v[2:3] op_sel:[1,0,0]
	v_pk_add_f32 v[6:7], v[6:7], v[38:39]
	v_pk_fma_f32 v[4:5], v[16:17], v[34:35], v[4:5] op_sel:[1,0,0]
	v_pk_fma_f32 v[0:1], v[16:17], v[30:31], v[0:1] op_sel:[1,0,0]
	v_mov_b32_e32 v51, v72
	v_mov_b32_e32 v64, v19
	v_pk_add_f32 v[6:7], v[6:7], v[50:51]
	v_pk_fma_f32 v[2:3], v[18:19], v[60:61], v[2:3] op_sel_hi:[0,1,1]
	v_pk_fma_f32 v[0:1], v[18:19], v[58:59], v[0:1] op_sel_hi:[0,1,1]
	v_pk_fma_f32 v[4:5], v[18:19], v[62:63], v[4:5] op_sel_hi:[0,1,1]
	v_mov_b32_e32 v75, v73
	v_pk_fma_f32 v[2:3], v[64:65], v[68:69], v[2:3] op_sel_hi:[0,1,1]
	v_pk_add_f32 v[6:7], v[6:7], v[74:75]
	v_pk_fma_f32 v[4:5], v[64:65], v[70:71], v[4:5] op_sel_hi:[0,1,1]
	v_pk_fma_f32 v[0:1], v[64:65], v[66:67], v[0:1] op_sel_hi:[0,1,1]
.LBB0_220:
	s_or_b64 exec, exec, s[24:25]
	v_and_b32_sdwa v27, v20, v56 dst_sel:DWORD dst_unused:UNUSED_PAD src0_sel:WORD_1 src1_sel:DWORD
	v_add3_u32 v28, v20, v27, s58
	v_and_b32_sdwa v27, v23, v56 dst_sel:DWORD dst_unused:UNUSED_PAD src0_sel:WORD_1 src1_sel:DWORD
	v_and_b32_sdwa v29, v21, v56 dst_sel:DWORD dst_unused:UNUSED_PAD src0_sel:WORD_1 src1_sel:DWORD
	v_and_b32_sdwa v26, v22, v56 dst_sel:DWORD dst_unused:UNUSED_PAD src0_sel:WORD_1 src1_sel:DWORD
	v_add3_u32 v27, v23, v27, s58
	v_add3_u32 v29, v21, v29, s58
	v_add3_u32 v26, v22, v26, s58
	v_and_b32_e32 v27, 0xffff0000, v27
	v_and_b32_e32 v29, 0xffff0000, v29
	v_or_b32_sdwa v27, v27, v26 dst_sel:DWORD dst_unused:UNUSED_PAD src0_sel:DWORD src1_sel:WORD_1
	v_or_b32_sdwa v26, v29, v28 dst_sel:DWORD dst_unused:UNUSED_PAD src0_sel:DWORD src1_sel:WORD_1
	global_store_dwordx2 v[24:25], v[26:27], off offset:1536
	s_and_saveexec_b64 s[24:25], s[6:7]
	s_cbranch_execz .LBB0_222
	v_add_u32_e32 v36, 0, v54
	ds_read_b128 v[24:27], v36 offset:16
	ds_read_b128 v[28:31], v57 offset:27680
	ds_read_b128 v[32:35], v57 offset:27696
	ds_read_b128 v[36:39], v36
	ds_read_b128 v[46:49], v57 offset:27712
	ds_read_b128 v[58:61], v57 offset:27728
	ds_read_b128 v[62:65], v57 offset:27744
	ds_read_b128 v[66:69], v57 offset:27760
	s_waitcnt lgkmcnt(7)
	v_mul_f32_e32 v26, v20, v26
	s_waitcnt lgkmcnt(5)
	v_mul_f32_e32 v50, v21, v34
	v_mov_b32_e32 v34, v27
	v_pk_mul_f32 v[34:35], v[20:21], v[34:35]
	s_waitcnt lgkmcnt(0)
	v_mul_f32_e32 v72, v23, v68
	v_mov_b32_e32 v68, v61
	v_mov_b32_e32 v27, v34
	v_pk_mul_f32 v[68:69], v[22:23], v[68:69]
	v_pk_fma_f32 v[4:5], v[20:21], v[24:25], v[4:5] op_sel_hi:[0,1,1]
	v_pk_add_f32 v[6:7], v[6:7], v[26:27]
	v_pk_fma_f32 v[2:3], v[20:21], v[38:39], v[2:3] op_sel_hi:[0,1,1]
	v_pk_fma_f32 v[0:1], v[20:21], v[36:37], v[0:1] op_sel_hi:[0,1,1]
	v_mov_b32_e32 v51, v35
	v_mul_f32_e32 v60, v22, v60
	v_pk_fma_f32 v[2:3], v[20:21], v[30:31], v[2:3] op_sel:[1,0,0]
	v_pk_add_f32 v[6:7], v[6:7], v[50:51]
	v_pk_fma_f32 v[4:5], v[20:21], v[32:33], v[4:5] op_sel:[1,0,0]
	v_pk_fma_f32 v[0:1], v[20:21], v[28:29], v[0:1] op_sel:[1,0,0]
	v_mov_b32_e32 v61, v68
	v_mov_b32_e32 v70, v23
	v_pk_add_f32 v[6:7], v[6:7], v[60:61]
	v_pk_fma_f32 v[2:3], v[22:23], v[48:49], v[2:3] op_sel_hi:[0,1,1]
	v_pk_fma_f32 v[0:1], v[22:23], v[46:47], v[0:1] op_sel_hi:[0,1,1]
	v_pk_fma_f32 v[4:5], v[22:23], v[58:59], v[4:5] op_sel_hi:[0,1,1]
	v_mov_b32_e32 v73, v69
	v_pk_fma_f32 v[2:3], v[70:71], v[64:65], v[2:3] op_sel_hi:[0,1,1]
	v_pk_add_f32 v[6:7], v[6:7], v[72:73]
	v_pk_fma_f32 v[4:5], v[70:71], v[66:67], v[4:5] op_sel_hi:[0,1,1]
	v_pk_fma_f32 v[0:1], v[70:71], v[62:63], v[0:1] op_sel_hi:[0,1,1]
